# hoist bias-rstd loads to epilogue top in P1 EpiT0, P8 EpiRowScale, P8 EpiT1 (single wait per tile)
# speedup vs baseline: 1.0142x; 1.0142x over previous
; __device__ __forceinline__ u32x4v pack8(const f32x4& a, const f32x4& b) { u32x4v w; w.x = cvt_pk_bf16(a[0], a[1]); w.y = cvt_pk_bf16(a[2], a[3]); w.z = cvt_pk_bf16(b[0], b[1]); w.w = cvt_pk_bf16(b[2], b[3]); return w; }
;     __device__ __forceinline__ void operator()(const f32x4 (&acc)[2][2][4][2], const Unit& u, int wr, int wc, int fr, int fq) const {
;     ...
;             for (int m = 0; m < 4; ++m) { const int r = row0 + ai * HALF + m * 16; const float rv = rvec[r]; bf16_t* rowp = O + (size_t)r * ldc + col0;
;                 const float rk = (MODE == 2) ? fabsf(rv) * kdec : 0.f;
; #pragma unroll
;                 for (int bj = 0; bj < 2; ++bj) { f32x4 v0 = acc[ai][bj][m][0], v1 = acc[ai][bj][m][1];
;                     if (MODE == 0) { v0 = v0 + rv; v1 = v1 + rv; }
;                     if (MODE == 1) { v0 = v0 * cs[bj][0] + rv; v1 = v1 * cs[bj][1] + rv; }
;                     if (MODE == 2) { const float cb = (float)(col0 + bj * HALF);
; #pragma unroll
;                         for (int e = 0; e < 4; ++e) { v0[e] *= __builtin_amdgcn_exp2f(-(cb + (float)e) * rk); v1[e] *= __builtin_amdgcn_exp2f(-(cb + (float)(4 + e)) * rk); } }
;                     if (MODE == 1) {
;                         const int mtok = col0 + bj * HALF; const size_t o = ((((size_t)(r >> 6) * 512 + (mtok >> 6)) * 8 + ((mtok & 63) >> 3)) * 64 + (r & 63)) * 8;
;                         *(u32x4v*)(O + o) = pack8(v0, v1);
;                     } else
;                     *(u32x4v*)(rowp + bj * HALF) = pack8(v0, v1); } }
.LBB0_237:
	v_lshl_add_u32 v164, s56, 8, v157
	v_ashrrev_i32_e32 v165, 31, v164
	v_lshl_add_u64 v[146:147], v[164:165], 2, s[46:47]
	global_load_dword v166, v[146:147], off
	global_load_dword v222, v[146:147], off offset:64
	global_load_dword v224, v[146:147], off offset:128
	global_load_dword v226, v[146:147], off offset:192
	global_load_dword v228, v[146:147], off offset:512
	global_load_dword v230, v[146:147], off offset:576
	global_load_dword v232, v[146:147], off offset:640
	global_load_dword v234, v[146:147], off offset:704
	v_lshl_or_b32 v144, s80, 8, v159
	v_ashrrev_i32_e32 v145, 31, v144
	v_lshlrev_b64 v[168:169], 16, v[164:165]
	v_lshlrev_b64 v[170:171], 1, v[144:145]
	v_lshl_add_u64 v[144:145], s[40:41], 0, v[168:169]
	v_lshl_add_u64 v[144:145], v[144:145], 0, v[170:171]
	s_mov_b32 s10, 0x800000
	s_mov_b64 s[6:7], 0x800000
	s_waitcnt vmcnt(0)
	v_pk_add_f32 v[126:127], v[126:127], v[166:167] op_sel_hi:[1,0]
	v_pk_add_f32 v[124:125], v[124:125], v[166:167] op_sel_hi:[1,0]
	v_pk_add_f32 v[122:123], v[122:123], v[166:167] op_sel_hi:[1,0]
	v_pk_add_f32 v[120:121], v[120:121], v[166:167] op_sel_hi:[1,0]
	v_pk_add_f32 v[118:119], v[118:119], v[166:167] op_sel_hi:[1,0]
	v_pk_add_f32 v[116:117], v[116:117], v[166:167] op_sel_hi:[1,0]
	v_pk_add_f32 v[168:169], v[114:115], v[166:167] op_sel_hi:[1,0]
	v_pk_add_f32 v[166:167], v[112:113], v[166:167] op_sel_hi:[1,0]
	v_cvt_pk_bf16_f32 v112, v124, v125
	v_cvt_pk_bf16_f32 v113, v126, v127
	v_cvt_pk_bf16_f32 v114, v120, v121
	v_cvt_pk_bf16_f32 v115, v122, v123
	global_store_dwordx4 v[144:145], v[112:115], off
	s_nop 1
	v_cvt_pk_bf16_f32 v112, v116, v117
	v_cvt_pk_bf16_f32 v113, v118, v119
	v_cvt_pk_bf16_f32 v114, v166, v167
	v_cvt_pk_bf16_f32 v115, v168, v169
	global_store_dwordx4 v[144:145], v[112:115], off offset:256
	s_nop 1
	v_pk_add_f32 v[110:111], v[110:111], v[222:223] op_sel_hi:[1,0]
	v_or_b32_e32 v114, 16, v164
	v_ashrrev_i32_e32 v115, 31, v114
	v_lshlrev_b64 v[114:115], 16, v[114:115]
	v_lshl_add_u64 v[114:115], s[40:41], 0, v[114:115]
	v_lshl_add_u64 v[114:115], v[114:115], 0, v[170:171]
	v_pk_add_f32 v[108:109], v[108:109], v[222:223] op_sel_hi:[1,0]
	v_pk_add_f32 v[106:107], v[106:107], v[222:223] op_sel_hi:[1,0]
	v_pk_add_f32 v[104:105], v[104:105], v[222:223] op_sel_hi:[1,0]
	v_pk_add_f32 v[102:103], v[102:103], v[222:223] op_sel_hi:[1,0]
	v_pk_add_f32 v[100:101], v[100:101], v[222:223] op_sel_hi:[1,0]
	v_pk_add_f32 v[116:117], v[98:99], v[222:223] op_sel_hi:[1,0]
	v_pk_add_f32 v[112:113], v[96:97], v[222:223] op_sel_hi:[1,0]
	v_cvt_pk_bf16_f32 v96, v108, v109
	v_cvt_pk_bf16_f32 v97, v110, v111
	v_cvt_pk_bf16_f32 v98, v104, v105
	v_cvt_pk_bf16_f32 v99, v106, v107
	global_store_dwordx4 v[114:115], v[96:99], off
	s_nop 1
	v_cvt_pk_bf16_f32 v96, v100, v101
	v_cvt_pk_bf16_f32 v97, v102, v103
	v_cvt_pk_bf16_f32 v98, v112, v113
	v_cvt_pk_bf16_f32 v99, v116, v117
	global_store_dwordx4 v[114:115], v[96:99], off offset:256
	s_nop 1
	v_pk_add_f32 v[94:95], v[94:95], v[224:225] op_sel_hi:[1,0]
	v_or_b32_e32 v98, 32, v164
	v_ashrrev_i32_e32 v99, 31, v98
	v_lshlrev_b64 v[98:99], 16, v[98:99]
	v_lshl_add_u64 v[98:99], s[40:41], 0, v[98:99]
	v_lshl_add_u64 v[98:99], v[98:99], 0, v[170:171]
	v_pk_add_f32 v[92:93], v[92:93], v[224:225] op_sel_hi:[1,0]
	v_pk_add_f32 v[90:91], v[90:91], v[224:225] op_sel_hi:[1,0]
	v_pk_add_f32 v[88:89], v[88:89], v[224:225] op_sel_hi:[1,0]
	v_pk_add_f32 v[86:87], v[86:87], v[224:225] op_sel_hi:[1,0]
	v_pk_add_f32 v[84:85], v[84:85], v[224:225] op_sel_hi:[1,0]
	v_pk_add_f32 v[100:101], v[82:83], v[224:225] op_sel_hi:[1,0]
	v_pk_add_f32 v[96:97], v[80:81], v[224:225] op_sel_hi:[1,0]
	v_cvt_pk_bf16_f32 v80, v92, v93
	v_cvt_pk_bf16_f32 v81, v94, v95
	v_cvt_pk_bf16_f32 v82, v88, v89
	v_cvt_pk_bf16_f32 v83, v90, v91
	global_store_dwordx4 v[98:99], v[80:83], off
	s_nop 1
	v_cvt_pk_bf16_f32 v80, v84, v85
	v_cvt_pk_bf16_f32 v81, v86, v87
	v_cvt_pk_bf16_f32 v82, v96, v97
	v_cvt_pk_bf16_f32 v83, v100, v101
	global_store_dwordx4 v[98:99], v[80:83], off offset:256
	s_nop 1
	v_pk_add_f32 v[78:79], v[78:79], v[226:227] op_sel_hi:[1,0]
	v_or_b32_e32 v82, 48, v164
	v_ashrrev_i32_e32 v83, 31, v82
	v_lshlrev_b64 v[82:83], 16, v[82:83]
	v_lshl_add_u64 v[82:83], s[40:41], 0, v[82:83]
	v_lshl_add_u64 v[82:83], v[82:83], 0, v[170:171]
	v_pk_add_f32 v[76:77], v[76:77], v[226:227] op_sel_hi:[1,0]
	v_pk_add_f32 v[74:75], v[74:75], v[226:227] op_sel_hi:[1,0]
	v_pk_add_f32 v[72:73], v[72:73], v[226:227] op_sel_hi:[1,0]
	v_pk_add_f32 v[70:71], v[70:71], v[226:227] op_sel_hi:[1,0]
	v_pk_add_f32 v[68:69], v[68:69], v[226:227] op_sel_hi:[1,0]
	v_pk_add_f32 v[84:85], v[66:67], v[226:227] op_sel_hi:[1,0]
	v_pk_add_f32 v[80:81], v[64:65], v[226:227] op_sel_hi:[1,0]
; __device__ __forceinline__ u32x4v pack8(const f32x4& a, const f32x4& b) { u32x4v w; w.x = cvt_pk_bf16(a[0], a[1]); w.y = cvt_pk_bf16(a[2], a[3]); w.z = cvt_pk_bf16(b[0], b[1]); w.w = cvt_pk_bf16(b[2], b[3]); return w; }
;     __device__ __forceinline__ void operator()(const f32x4 (&acc)[2][2][4][2], const Unit& u, int wr, int wc, int fr, int fq) const {
;     ...
;             for (int m = 0; m < 4; ++m) { const int r = row0 + ai * HALF + m * 16; const float rv = rvec[r]; bf16_t* rowp = O + (size_t)r * ldc + col0;
;                 const float rk = (MODE == 2) ? fabsf(rv) * kdec : 0.f;
; #pragma unroll
;                 for (int bj = 0; bj < 2; ++bj) { f32x4 v0 = acc[ai][bj][m][0], v1 = acc[ai][bj][m][1];
;                     if (MODE == 0) { v0 = v0 + rv; v1 = v1 + rv; }
;                     if (MODE == 1) { v0 = v0 * cs[bj][0] + rv; v1 = v1 * cs[bj][1] + rv; }
;                     if (MODE == 2) { const float cb = (float)(col0 + bj * HALF);
; #pragma unroll
;                         for (int e = 0; e < 4; ++e) { v0[e] *= __builtin_amdgcn_exp2f(-(cb + (float)e) * rk); v1[e] *= __builtin_amdgcn_exp2f(-(cb + (float)(4 + e)) * rk); } }
;                     if (MODE == 1) {
;                         const int mtok = col0 + bj * HALF; const size_t o = ((((size_t)(r >> 6) * 512 + (mtok >> 6)) * 8 + ((mtok & 63) >> 3)) * 64 + (r & 63)) * 8;
;                         *(u32x4v*)(O + o) = pack8(v0, v1);
;                     } else
;                     *(u32x4v*)(rowp + bj * HALF) = pack8(v0, v1); } }
	v_cvt_pk_bf16_f32 v64, v76, v77
	v_cvt_pk_bf16_f32 v65, v78, v79
	v_cvt_pk_bf16_f32 v66, v72, v73
	v_cvt_pk_bf16_f32 v67, v74, v75
	global_store_dwordx4 v[82:83], v[64:67], off
	s_nop 1
	v_cvt_pk_bf16_f32 v64, v68, v69
	v_cvt_pk_bf16_f32 v65, v70, v71
	v_cvt_pk_bf16_f32 v66, v80, v81
	v_cvt_pk_bf16_f32 v67, v84, v85
	global_store_dwordx4 v[82:83], v[64:67], off offset:256
	s_nop 1
	v_add_co_u32_e32 v68, vcc, s10, v144
	v_lshl_add_u64 v[66:67], v[144:145], 0, s[6:7]
	s_nop 0
	v_addc_co_u32_e32 v69, vcc, 0, v145, vcc
	s_mov_b32 s10, 0x900000
	s_mov_b64 s[6:7], 0x900000
	v_pk_add_f32 v[62:63], v[62:63], v[228:229] op_sel_hi:[1,0]
	v_pk_add_f32 v[60:61], v[60:61], v[228:229] op_sel_hi:[1,0]
	v_pk_add_f32 v[58:59], v[58:59], v[228:229] op_sel_hi:[1,0]
	v_pk_add_f32 v[56:57], v[56:57], v[228:229] op_sel_hi:[1,0]
	v_pk_add_f32 v[54:55], v[54:55], v[228:229] op_sel_hi:[1,0]
	v_pk_add_f32 v[52:53], v[52:53], v[228:229] op_sel_hi:[1,0]
	v_pk_add_f32 v[70:71], v[50:51], v[228:229] op_sel_hi:[1,0]
	v_pk_add_f32 v[64:65], v[48:49], v[228:229] op_sel_hi:[1,0]
	v_cvt_pk_bf16_f32 v48, v60, v61
	v_cvt_pk_bf16_f32 v49, v62, v63
	v_cvt_pk_bf16_f32 v50, v56, v57
	v_cvt_pk_bf16_f32 v51, v58, v59
	global_store_dwordx4 v[68:69], v[48:51], off
	s_nop 1
	v_cvt_pk_bf16_f32 v48, v52, v53
	v_cvt_pk_bf16_f32 v49, v54, v55
	v_cvt_pk_bf16_f32 v50, v64, v65
	v_cvt_pk_bf16_f32 v51, v70, v71
	global_store_dwordx4 v[66:67], v[48:51], off offset:256
	s_nop 1
	v_add_co_u32_e32 v52, vcc, s10, v144
	v_lshl_add_u64 v[50:51], v[144:145], 0, s[6:7]
	s_nop 0
	v_addc_co_u32_e32 v53, vcc, 0, v145, vcc
	s_mov_b32 s10, 0xa00000
	s_mov_b64 s[6:7], 0xa00000
	v_pk_add_f32 v[46:47], v[46:47], v[230:231] op_sel_hi:[1,0]
	v_pk_add_f32 v[44:45], v[44:45], v[230:231] op_sel_hi:[1,0]
	v_pk_add_f32 v[42:43], v[42:43], v[230:231] op_sel_hi:[1,0]
	v_pk_add_f32 v[40:41], v[40:41], v[230:231] op_sel_hi:[1,0]
	v_pk_add_f32 v[38:39], v[38:39], v[230:231] op_sel_hi:[1,0]
	v_pk_add_f32 v[36:37], v[36:37], v[230:231] op_sel_hi:[1,0]
	v_pk_add_f32 v[54:55], v[34:35], v[230:231] op_sel_hi:[1,0]
	v_pk_add_f32 v[48:49], v[32:33], v[230:231] op_sel_hi:[1,0]
	v_cvt_pk_bf16_f32 v32, v44, v45
	v_cvt_pk_bf16_f32 v33, v46, v47
	v_cvt_pk_bf16_f32 v34, v40, v41
	v_cvt_pk_bf16_f32 v35, v42, v43
	global_store_dwordx4 v[52:53], v[32:35], off
	s_nop 1
	v_cvt_pk_bf16_f32 v32, v36, v37
	v_cvt_pk_bf16_f32 v33, v38, v39
	v_cvt_pk_bf16_f32 v34, v48, v49
	v_cvt_pk_bf16_f32 v35, v54, v55
	global_store_dwordx4 v[50:51], v[32:35], off offset:256
	s_nop 1
	v_add_co_u32_e32 v36, vcc, s10, v144
	v_lshl_add_u64 v[34:35], v[144:145], 0, s[6:7]
	s_nop 0
	v_addc_co_u32_e32 v37, vcc, 0, v145, vcc
	s_andn2_b64 vcc, exec, s[0:1]
	s_mov_b64 s[6:7], 0xb00000
	v_pk_add_f32 v[30:31], v[30:31], v[232:233] op_sel_hi:[1,0]
	v_pk_add_f32 v[28:29], v[28:29], v[232:233] op_sel_hi:[1,0]
	v_pk_add_f32 v[26:27], v[26:27], v[232:233] op_sel_hi:[1,0]
	v_pk_add_f32 v[24:25], v[24:25], v[232:233] op_sel_hi:[1,0]
	v_pk_add_f32 v[22:23], v[22:23], v[232:233] op_sel_hi:[1,0]
	v_pk_add_f32 v[20:21], v[20:21], v[232:233] op_sel_hi:[1,0]
	v_pk_add_f32 v[38:39], v[18:19], v[232:233] op_sel_hi:[1,0]
	v_pk_add_f32 v[32:33], v[16:17], v[232:233] op_sel_hi:[1,0]
	v_cvt_pk_bf16_f32 v16, v28, v29
	v_cvt_pk_bf16_f32 v17, v30, v31
	v_cvt_pk_bf16_f32 v18, v24, v25
	v_cvt_pk_bf16_f32 v19, v26, v27
	global_store_dwordx4 v[36:37], v[16:19], off
	s_nop 1
	v_cvt_pk_bf16_f32 v16, v20, v21
	v_cvt_pk_bf16_f32 v17, v22, v23
	v_cvt_pk_bf16_f32 v18, v32, v33
	v_cvt_pk_bf16_f32 v19, v38, v39
	global_store_dwordx4 v[34:35], v[16:19], off offset:256
	s_nop 1
	v_add_co_u32_e64 v20, s[0:1], s79, v144
	v_lshl_add_u64 v[18:19], v[144:145], 0, s[6:7]
	s_nop 0
	v_addc_co_u32_e64 v21, s[0:1], 0, v145, s[0:1]
	s_mov_b64 s[0:1], -1
	v_pk_add_f32 v[14:15], v[14:15], v[234:235] op_sel_hi:[1,0]
	v_pk_add_f32 v[12:13], v[12:13], v[234:235] op_sel_hi:[1,0]
	v_pk_add_f32 v[10:11], v[10:11], v[234:235] op_sel_hi:[1,0]
	v_pk_add_f32 v[8:9], v[8:9], v[234:235] op_sel_hi:[1,0]
	v_pk_add_f32 v[6:7], v[6:7], v[234:235] op_sel_hi:[1,0]
	v_pk_add_f32 v[4:5], v[4:5], v[234:235] op_sel_hi:[1,0]
	v_pk_add_f32 v[22:23], v[2:3], v[234:235] op_sel_hi:[1,0]
	v_pk_add_f32 v[16:17], v[0:1], v[234:235] op_sel_hi:[1,0]
	v_cvt_pk_bf16_f32 v0, v12, v13
	v_cvt_pk_bf16_f32 v1, v14, v15
	v_cvt_pk_bf16_f32 v2, v8, v9
	v_cvt_pk_bf16_f32 v3, v10, v11
	global_store_dwordx4 v[20:21], v[0:3], off
	s_nop 1
	v_cvt_pk_bf16_f32 v0, v4, v5
	v_cvt_pk_bf16_f32 v1, v6, v7
	v_cvt_pk_bf16_f32 v2, v16, v17
	v_cvt_pk_bf16_f32 v3, v22, v23
	global_store_dwordx4 v[18:19], v[0:3], off offset:256
	s_cbranch_vccnz .LBB0_230
	s_andn2_b64 vcc, exec, s[8:9]
	s_cbranch_vccnz .LBB0_229
	s_barrier
	s_branch .LBB0_229

; __device__ __forceinline__ u32x4v pack8(const f32x4& a, const f32x4& b) { u32x4v w; w.x = cvt_pk_bf16(a[0], a[1]); w.y = cvt_pk_bf16(a[2], a[3]); w.z = cvt_pk_bf16(b[0], b[1]); w.w = cvt_pk_bf16(b[2], b[3]); return w; }
;     __device__ __forceinline__ void operator()(const f32x4 (&acc)[2][2][4][2], const Unit& u, int wr, int wc, int fr, int fq) const {
;         const int row0 = u.pm * BM + wr * 64 + fr, col0 = u.pn * BM + wc * 32 + 8 * fq;
;         f32x4 bv[2][2];
; #pragma unroll
;         for (int bj = 0; bj < 2; ++bj)
; #pragma unroll
;             for (int n = 0; n < 2; ++n) bv[bj][n] = *(const f32x4*)(bias + col0 + bj * HALF + 4 * n);
; #pragma unroll
;         for (int ai = 0; ai < 2; ++ai)
; #pragma unroll
;             for (int m = 0; m < 4; ++m) { const int r = row0 + ai * HALF + m * 16; const float rs = rstd[r]; bf16_t* rowp = O + (size_t)r * ldc + col0;
; #pragma unroll
;                 for (int bj = 0; bj < 2; ++bj) { const f32x4 v0 = acc[ai][bj][m][0] * rs + bv[bj][0], v1 = acc[ai][bj][m][1] * rs + bv[bj][1];
;                     const int c = col0 + bj * HALF;
;                     (void)rowp; *(u32x4v*)(O + (((size_t)(c >> 6) * 2 + ((c >> 5) & 1)) * 32768 + r) * 32 + (c & 31)) = pack8(v0, v1); } }
.LBB0_817:
	s_lshl_b32 s6, s35, 8
	s_or_b32 s6, s6, s50
	v_or_b32_e32 v128, s6, v144
	v_lshl_add_u32 v164, s34, 8, v174
	v_ashrrev_i32_e32 v129, 31, v128
	v_ashrrev_i32_e32 v165, 31, v164
	v_lshl_add_u64 v[128:129], v[128:129], 2, s[22:23]
	v_lshl_add_u64 v[166:167], v[164:165], 2, s[8:9]
	global_load_dword v180, v[166:167], off
	global_load_dword v222, v[166:167], off offset:64
	global_load_dword v224, v[166:167], off offset:128
	global_load_dword v226, v[166:167], off offset:192
	global_load_dword v228, v[166:167], off offset:512
	global_load_dword v230, v[166:167], off offset:576
	global_load_dword v232, v[166:167], off offset:640
	global_load_dword v234, v[166:167], off offset:704
	global_load_dwordx4 v[140:143], v[128:129], off
	global_load_dwordx4 v[136:139], v[128:129], off offset:16
	global_load_dwordx4 v[132:135], v[128:129], off offset:512
	s_nop 0
	global_load_dwordx4 v[128:131], v[128:129], off offset:528
	s_ashr_i32 s10, s6, 6
	s_ashr_i32 s11, s10, 31
	s_lshl_b64 s[6:7], s[10:11], 22
	s_add_u32 s6, s40, s6
	s_addc_u32 s7, s41, s7
	s_or_b32 s10, s10, 2
	s_ashr_i32 s11, s10, 31
	s_lshl_b64 s[10:11], s[10:11], 22
	v_lshl_add_u64 v[184:185], v[164:165], 0, s[12:13]
	s_add_u32 s34, s40, s10
	v_lshlrev_b64 v[184:185], 6, v[184:185]
	s_addc_u32 s35, s41, s11
	v_or_b32_e32 v182, 16, v164
	v_lshl_add_u64 v[188:189], s[6:7], 0, v[184:185]
	v_lshl_add_u64 v[184:185], s[34:35], 0, v[184:185]
	v_ashrrev_i32_e32 v183, 31, v182
	v_lshl_add_u64 v[188:189], v[188:189], 0, v[154:155]
	v_lshl_add_u64 v[184:185], v[184:185], 0, v[154:155]
	v_lshl_add_u64 v[186:187], v[182:183], 2, s[8:9]
	s_andn2_b64 vcc, exec, s[0:1]
	s_mov_b64 s[0:1], -1
	s_waitcnt vmcnt(0)
	v_pk_fma_f32 v[126:127], v[126:127], v[180:181], v[142:143] op_sel_hi:[1,0,1]
	v_pk_fma_f32 v[124:125], v[124:125], v[180:181], v[140:141] op_sel_hi:[1,0,1]
	v_pk_fma_f32 v[122:123], v[122:123], v[180:181], v[138:139] op_sel_hi:[1,0,1]
	v_pk_fma_f32 v[120:121], v[120:121], v[180:181], v[136:137] op_sel_hi:[1,0,1]
	v_pk_fma_f32 v[118:119], v[118:119], v[180:181], v[134:135] op_sel_hi:[1,0,1]
	v_pk_fma_f32 v[116:117], v[116:117], v[180:181], v[132:133] op_sel_hi:[1,0,1]
	v_pk_fma_f32 v[190:191], v[114:115], v[180:181], v[130:131] op_sel_hi:[1,0,1]
	v_pk_fma_f32 v[180:181], v[112:113], v[180:181], v[128:129] op_sel_hi:[1,0,1]
	v_cvt_pk_bf16_f32 v112, v124, v125
	v_cvt_pk_bf16_f32 v113, v126, v127
	v_cvt_pk_bf16_f32 v114, v120, v121
	v_cvt_pk_bf16_f32 v115, v122, v123
	global_store_dwordx4 v[188:189], v[112:115], off
	s_nop 1
	v_cvt_pk_bf16_f32 v112, v116, v117
	v_cvt_pk_bf16_f32 v113, v118, v119
	v_cvt_pk_bf16_f32 v114, v180, v181
	v_cvt_pk_bf16_f32 v115, v190, v191
	global_store_dwordx4 v[184:185], v[112:115], off
	s_nop 1
	v_lshl_add_u64 v[116:117], v[182:183], 0, s[12:13]
	v_lshlrev_b64 v[116:117], 6, v[116:117]
	v_or_b32_e32 v114, 32, v164
	v_lshl_add_u64 v[120:121], s[6:7], 0, v[116:117]
	v_lshl_add_u64 v[116:117], s[34:35], 0, v[116:117]
	v_ashrrev_i32_e32 v115, 31, v114
	v_lshl_add_u64 v[120:121], v[120:121], 0, v[154:155]
	v_lshl_add_u64 v[116:117], v[116:117], 0, v[154:155]
	v_lshl_add_u64 v[118:119], v[114:115], 2, s[8:9]
	v_pk_fma_f32 v[110:111], v[110:111], v[222:223], v[142:143] op_sel_hi:[1,0,1]
	v_pk_fma_f32 v[108:109], v[108:109], v[222:223], v[140:141] op_sel_hi:[1,0,1]
	v_pk_fma_f32 v[106:107], v[106:107], v[222:223], v[138:139] op_sel_hi:[1,0,1]
	v_pk_fma_f32 v[104:105], v[104:105], v[222:223], v[136:137] op_sel_hi:[1,0,1]
	v_pk_fma_f32 v[102:103], v[102:103], v[222:223], v[134:135] op_sel_hi:[1,0,1]
	v_pk_fma_f32 v[100:101], v[100:101], v[222:223], v[132:133] op_sel_hi:[1,0,1]
	v_pk_fma_f32 v[122:123], v[98:99], v[222:223], v[130:131] op_sel_hi:[1,0,1]
	v_pk_fma_f32 v[112:113], v[96:97], v[222:223], v[128:129] op_sel_hi:[1,0,1]
	v_cvt_pk_bf16_f32 v96, v108, v109
	v_cvt_pk_bf16_f32 v97, v110, v111
	v_cvt_pk_bf16_f32 v98, v104, v105
	v_cvt_pk_bf16_f32 v99, v106, v107
	global_store_dwordx4 v[120:121], v[96:99], off
	s_nop 1
	v_cvt_pk_bf16_f32 v96, v100, v101
	v_cvt_pk_bf16_f32 v97, v102, v103
	v_cvt_pk_bf16_f32 v98, v112, v113
	v_cvt_pk_bf16_f32 v99, v122, v123
	global_store_dwordx4 v[116:117], v[96:99], off
	s_nop 1
	v_lshl_add_u64 v[100:101], v[114:115], 0, s[12:13]
	v_lshlrev_b64 v[100:101], 6, v[100:101]
	v_or_b32_e32 v98, 48, v164
	v_lshl_add_u64 v[104:105], s[6:7], 0, v[100:101]
	v_lshl_add_u64 v[100:101], s[34:35], 0, v[100:101]
	v_ashrrev_i32_e32 v99, 31, v98
	v_lshl_add_u64 v[104:105], v[104:105], 0, v[154:155]
	v_lshl_add_u64 v[100:101], v[100:101], 0, v[154:155]
	v_lshl_add_u64 v[102:103], v[98:99], 2, s[8:9]
	v_pk_fma_f32 v[94:95], v[94:95], v[224:225], v[142:143] op_sel_hi:[1,0,1]
	v_pk_fma_f32 v[92:93], v[92:93], v[224:225], v[140:141] op_sel_hi:[1,0,1]
	v_pk_fma_f32 v[90:91], v[90:91], v[224:225], v[138:139] op_sel_hi:[1,0,1]
	v_pk_fma_f32 v[88:89], v[88:89], v[224:225], v[136:137] op_sel_hi:[1,0,1]
	v_pk_fma_f32 v[86:87], v[86:87], v[224:225], v[134:135] op_sel_hi:[1,0,1]
	v_pk_fma_f32 v[84:85], v[84:85], v[224:225], v[132:133] op_sel_hi:[1,0,1]
	v_pk_fma_f32 v[106:107], v[82:83], v[224:225], v[130:131] op_sel_hi:[1,0,1]
	v_pk_fma_f32 v[96:97], v[80:81], v[224:225], v[128:129] op_sel_hi:[1,0,1]
	v_cvt_pk_bf16_f32 v80, v92, v93
	v_cvt_pk_bf16_f32 v81, v94, v95
	v_cvt_pk_bf16_f32 v82, v88, v89
	v_cvt_pk_bf16_f32 v83, v90, v91
	global_store_dwordx4 v[104:105], v[80:83], off
	s_nop 1
	v_cvt_pk_bf16_f32 v80, v84, v85
	v_cvt_pk_bf16_f32 v81, v86, v87
	v_cvt_pk_bf16_f32 v82, v96, v97
	v_cvt_pk_bf16_f32 v83, v106, v107
	global_store_dwordx4 v[100:101], v[80:83], off
	s_nop 1
	v_pk_fma_f32 v[78:79], v[78:79], v[226:227], v[142:143] op_sel_hi:[1,0,1]
; __device__ __forceinline__ u32x4v pack8(const f32x4& a, const f32x4& b) { u32x4v w; w.x = cvt_pk_bf16(a[0], a[1]); w.y = cvt_pk_bf16(a[2], a[3]); w.z = cvt_pk_bf16(b[0], b[1]); w.w = cvt_pk_bf16(b[2], b[3]); return w; }
;     __device__ __forceinline__ void operator()(const f32x4 (&acc)[2][2][4][2], const Unit& u, int wr, int wc, int fr, int fq) const {
;     ...
;         for (int ai = 0; ai < 2; ++ai)
; #pragma unroll
;             for (int m = 0; m < 4; ++m) { const int r = row0 + ai * HALF + m * 16; const float rs = rstd[r]; bf16_t* rowp = O + (size_t)r * ldc + col0;
; #pragma unroll
;                 for (int bj = 0; bj < 2; ++bj) { const f32x4 v0 = acc[ai][bj][m][0] * rs + bv[bj][0], v1 = acc[ai][bj][m][1] * rs + bv[bj][1];
;                     const int c = col0 + bj * HALF;
;                     (void)rowp; *(u32x4v*)(O + (((size_t)(c >> 6) * 2 + ((c >> 5) & 1)) * 32768 + r) * 32 + (c & 31)) = pack8(v0, v1); } }
	v_lshl_add_u64 v[82:83], v[98:99], 0, s[12:13]
	v_lshlrev_b64 v[82:83], 6, v[82:83]
	v_lshl_add_u64 v[84:85], s[6:7], 0, v[82:83]
	v_lshl_add_u64 v[82:83], s[34:35], 0, v[82:83]
	v_lshl_add_u64 v[84:85], v[84:85], 0, v[154:155]
	v_lshl_add_u64 v[82:83], v[82:83], 0, v[154:155]
	v_pk_fma_f32 v[76:77], v[76:77], v[226:227], v[140:141] op_sel_hi:[1,0,1]
	v_pk_fma_f32 v[74:75], v[74:75], v[226:227], v[138:139] op_sel_hi:[1,0,1]
	v_pk_fma_f32 v[72:73], v[72:73], v[226:227], v[136:137] op_sel_hi:[1,0,1]
	v_pk_fma_f32 v[70:71], v[70:71], v[226:227], v[134:135] op_sel_hi:[1,0,1]
	v_pk_fma_f32 v[68:69], v[68:69], v[226:227], v[132:133] op_sel_hi:[1,0,1]
	v_pk_fma_f32 v[86:87], v[66:67], v[226:227], v[130:131] op_sel_hi:[1,0,1]
	v_pk_fma_f32 v[80:81], v[64:65], v[226:227], v[128:129] op_sel_hi:[1,0,1]
	v_cvt_pk_bf16_f32 v64, v76, v77
	v_cvt_pk_bf16_f32 v65, v78, v79
	v_cvt_pk_bf16_f32 v66, v72, v73
	v_cvt_pk_bf16_f32 v67, v74, v75
	global_store_dwordx4 v[84:85], v[64:67], off
	s_nop 1
	v_cvt_pk_bf16_f32 v64, v68, v69
	v_cvt_pk_bf16_f32 v65, v70, v71
	v_cvt_pk_bf16_f32 v66, v80, v81
	v_cvt_pk_bf16_f32 v67, v86, v87
	global_store_dwordx4 v[82:83], v[64:67], off
	s_nop 1
	v_pk_fma_f32 v[62:63], v[62:63], v[228:229], v[142:143] op_sel_hi:[1,0,1]
	v_add_u32_e32 v66, 0x80, v164
	v_ashrrev_i32_e32 v67, 31, v66
	v_lshl_add_u64 v[66:67], v[66:67], 0, s[12:13]
	v_lshlrev_b64 v[66:67], 6, v[66:67]
	v_lshl_add_u64 v[68:69], s[6:7], 0, v[66:67]
	v_lshl_add_u64 v[66:67], s[34:35], 0, v[66:67]
	v_lshl_add_u64 v[68:69], v[68:69], 0, v[154:155]
	v_lshl_add_u64 v[66:67], v[66:67], 0, v[154:155]
	v_pk_fma_f32 v[60:61], v[60:61], v[228:229], v[140:141] op_sel_hi:[1,0,1]
	v_pk_fma_f32 v[58:59], v[58:59], v[228:229], v[138:139] op_sel_hi:[1,0,1]
	v_pk_fma_f32 v[56:57], v[56:57], v[228:229], v[136:137] op_sel_hi:[1,0,1]
	v_pk_fma_f32 v[54:55], v[54:55], v[228:229], v[134:135] op_sel_hi:[1,0,1]
	v_pk_fma_f32 v[52:53], v[52:53], v[228:229], v[132:133] op_sel_hi:[1,0,1]
	v_pk_fma_f32 v[70:71], v[50:51], v[228:229], v[130:131] op_sel_hi:[1,0,1]
	v_pk_fma_f32 v[64:65], v[48:49], v[228:229], v[128:129] op_sel_hi:[1,0,1]
	v_cvt_pk_bf16_f32 v48, v60, v61
	v_cvt_pk_bf16_f32 v49, v62, v63
	v_cvt_pk_bf16_f32 v50, v56, v57
	v_cvt_pk_bf16_f32 v51, v58, v59
	global_store_dwordx4 v[68:69], v[48:51], off
	s_nop 1
	v_cvt_pk_bf16_f32 v48, v52, v53
	v_cvt_pk_bf16_f32 v49, v54, v55
	v_cvt_pk_bf16_f32 v50, v64, v65
	v_cvt_pk_bf16_f32 v51, v70, v71
	global_store_dwordx4 v[66:67], v[48:51], off
	s_nop 1
	v_pk_fma_f32 v[46:47], v[46:47], v[230:231], v[142:143] op_sel_hi:[1,0,1]
	v_add_u32_e32 v50, 0x90, v164
	v_ashrrev_i32_e32 v51, 31, v50
	v_lshl_add_u64 v[50:51], v[50:51], 0, s[12:13]
	v_lshlrev_b64 v[50:51], 6, v[50:51]
	v_lshl_add_u64 v[52:53], s[6:7], 0, v[50:51]
	v_lshl_add_u64 v[50:51], s[34:35], 0, v[50:51]
	v_lshl_add_u64 v[52:53], v[52:53], 0, v[154:155]
	v_lshl_add_u64 v[50:51], v[50:51], 0, v[154:155]
	v_pk_fma_f32 v[44:45], v[44:45], v[230:231], v[140:141] op_sel_hi:[1,0,1]
	v_pk_fma_f32 v[42:43], v[42:43], v[230:231], v[138:139] op_sel_hi:[1,0,1]
	v_pk_fma_f32 v[40:41], v[40:41], v[230:231], v[136:137] op_sel_hi:[1,0,1]
	v_pk_fma_f32 v[38:39], v[38:39], v[230:231], v[134:135] op_sel_hi:[1,0,1]
	v_pk_fma_f32 v[36:37], v[36:37], v[230:231], v[132:133] op_sel_hi:[1,0,1]
	v_pk_fma_f32 v[54:55], v[34:35], v[230:231], v[130:131] op_sel_hi:[1,0,1]
	v_pk_fma_f32 v[48:49], v[32:33], v[230:231], v[128:129] op_sel_hi:[1,0,1]
	v_cvt_pk_bf16_f32 v32, v44, v45
	v_cvt_pk_bf16_f32 v33, v46, v47
	v_cvt_pk_bf16_f32 v34, v40, v41
	v_cvt_pk_bf16_f32 v35, v42, v43
	global_store_dwordx4 v[52:53], v[32:35], off
	s_nop 1
	v_cvt_pk_bf16_f32 v32, v36, v37
	v_cvt_pk_bf16_f32 v33, v38, v39
	v_cvt_pk_bf16_f32 v34, v48, v49
	v_cvt_pk_bf16_f32 v35, v54, v55
	global_store_dwordx4 v[50:51], v[32:35], off
	s_nop 1
	v_pk_fma_f32 v[30:31], v[30:31], v[232:233], v[142:143] op_sel_hi:[1,0,1]
	v_add_u32_e32 v34, 0xa0, v164
	v_ashrrev_i32_e32 v35, 31, v34
	v_lshl_add_u64 v[34:35], v[34:35], 0, s[12:13]
	v_lshlrev_b64 v[34:35], 6, v[34:35]
	v_lshl_add_u64 v[36:37], s[6:7], 0, v[34:35]
	v_lshl_add_u64 v[34:35], s[34:35], 0, v[34:35]
	v_lshl_add_u64 v[36:37], v[36:37], 0, v[154:155]
	v_lshl_add_u64 v[34:35], v[34:35], 0, v[154:155]
	v_pk_fma_f32 v[28:29], v[28:29], v[232:233], v[140:141] op_sel_hi:[1,0,1]
	v_pk_fma_f32 v[26:27], v[26:27], v[232:233], v[138:139] op_sel_hi:[1,0,1]
	v_pk_fma_f32 v[24:25], v[24:25], v[232:233], v[136:137] op_sel_hi:[1,0,1]
	v_pk_fma_f32 v[22:23], v[22:23], v[232:233], v[134:135] op_sel_hi:[1,0,1]
	v_pk_fma_f32 v[20:21], v[20:21], v[232:233], v[132:133] op_sel_hi:[1,0,1]
	v_pk_fma_f32 v[38:39], v[18:19], v[232:233], v[130:131] op_sel_hi:[1,0,1]
	v_pk_fma_f32 v[32:33], v[16:17], v[232:233], v[128:129] op_sel_hi:[1,0,1]
	v_cvt_pk_bf16_f32 v16, v28, v29
	v_cvt_pk_bf16_f32 v17, v30, v31
	v_cvt_pk_bf16_f32 v18, v24, v25
	v_cvt_pk_bf16_f32 v19, v26, v27
	global_store_dwordx4 v[36:37], v[16:19], off
	s_nop 1
	v_cvt_pk_bf16_f32 v16, v20, v21
	v_cvt_pk_bf16_f32 v17, v22, v23
	v_cvt_pk_bf16_f32 v18, v32, v33
	v_cvt_pk_bf16_f32 v19, v38, v39
	global_store_dwordx4 v[34:35], v[16:19], off
	s_nop 1
	v_pk_fma_f32 v[14:15], v[14:15], v[234:235], v[142:143] op_sel_hi:[1,0,1]
	v_add_u32_e32 v18, 0xb0, v164
	v_ashrrev_i32_e32 v19, 31, v18
	v_lshl_add_u64 v[18:19], v[18:19], 0, s[12:13]
	v_lshlrev_b64 v[18:19], 6, v[18:19]
	v_lshl_add_u64 v[20:21], s[6:7], 0, v[18:19]
	v_lshl_add_u64 v[18:19], s[34:35], 0, v[18:19]
	v_lshl_add_u64 v[20:21], v[20:21], 0, v[154:155]
	v_lshl_add_u64 v[18:19], v[18:19], 0, v[154:155]
	v_pk_fma_f32 v[12:13], v[12:13], v[234:235], v[140:141] op_sel_hi:[1,0,1]
	v_pk_fma_f32 v[10:11], v[10:11], v[234:235], v[138:139] op_sel_hi:[1,0,1]
	v_pk_fma_f32 v[8:9], v[8:9], v[234:235], v[136:137] op_sel_hi:[1,0,1]
	v_pk_fma_f32 v[6:7], v[6:7], v[234:235], v[134:135] op_sel_hi:[1,0,1]
	v_pk_fma_f32 v[4:5], v[4:5], v[234:235], v[132:133] op_sel_hi:[1,0,1]
	v_pk_fma_f32 v[22:23], v[2:3], v[234:235], v[130:131] op_sel_hi:[1,0,1]
	v_pk_fma_f32 v[16:17], v[0:1], v[234:235], v[128:129] op_sel_hi:[1,0,1]
	v_cvt_pk_bf16_f32 v0, v12, v13
	v_cvt_pk_bf16_f32 v1, v14, v15
	v_cvt_pk_bf16_f32 v2, v8, v9
	v_cvt_pk_bf16_f32 v3, v10, v11
	global_store_dwordx4 v[20:21], v[0:3], off
	s_nop 1
	v_cvt_pk_bf16_f32 v0, v4, v5
	v_cvt_pk_bf16_f32 v1, v6, v7
	v_cvt_pk_bf16_f32 v2, v16, v17
	v_cvt_pk_bf16_f32 v3, v22, v23
	global_store_dwordx4 v[18:19], v[0:3], off
	s_cbranch_vccnz .LBB0_806
	s_andn2_b64 vcc, exec, s[14:15]
	s_cbranch_vccnz .LBB0_805
	s_barrier
	s_branch .LBB0_805

; __device__ __forceinline__ u32x4v pack8(const f32x4& a, const f32x4& b) { u32x4v w; w.x = cvt_pk_bf16(a[0], a[1]); w.y = cvt_pk_bf16(a[2], a[3]); w.z = cvt_pk_bf16(b[0], b[1]); w.w = cvt_pk_bf16(b[2], b[3]); return w; }
;     __device__ __forceinline__ void operator()(const f32x4 (&acc)[2][2][4][2], const Unit& u, int wr, int wc, int fr, int fq) const {
;     ...
;         if (MODE == 1) {
; #pragma unroll
;             for (int bj = 0; bj < 2; ++bj)
; #pragma unroll
;                 for (int n = 0; n < 2; ++n) cs[bj][n] = *(const f32x4*)(cscale + col0 + bj * HALF + 4 * n);
;         }
; #pragma unroll
;         for (int ai = 0; ai < 2; ++ai)
; #pragma unroll
;             for (int m = 0; m < 4; ++m) { const int r = row0 + ai * HALF + m * 16; const float rv = rvec[r]; bf16_t* rowp = O + (size_t)r * ldc + col0;
;                 const float rk = (MODE == 2) ? fabsf(rv) * kdec : 0.f;
; #pragma unroll
;                 for (int bj = 0; bj < 2; ++bj) { f32x4 v0 = acc[ai][bj][m][0], v1 = acc[ai][bj][m][1];
;                     if (MODE == 0) { v0 = v0 + rv; v1 = v1 + rv; }
;                     if (MODE == 1) { v0 = v0 * cs[bj][0] + rv; v1 = v1 * cs[bj][1] + rv; }
;                     if (MODE == 2) { const float cb = (float)(col0 + bj * HALF);
; #pragma unroll
;                         for (int e = 0; e < 4; ++e) { v0[e] *= __builtin_amdgcn_exp2f(-(cb + (float)e) * rk); v1[e] *= __builtin_amdgcn_exp2f(-(cb + (float)(4 + e)) * rk); } }
;                     if (MODE == 1) {
;                         const int mtok = col0 + bj * HALF; const size_t o = ((((size_t)(r >> 6) * 512 + (mtok >> 6)) * 8 + ((mtok & 63) >> 3)) * 64 + (r & 63)) * 8;
;                         *(u32x4v*)(O + o) = pack8(v0, v1);
.LBB0_841:
	s_lshl_b32 s6, s28, 8
	s_lshl_b32 s7, s29, 8
	s_add_i32 s6, s6, s51
	s_or_b32 s7, s7, s52
	v_or_b32_e32 v174, s7, v144
	v_or_b32_e32 v168, s6, v145
	v_ashrrev_i32_e32 v175, 31, v174
	v_ashrrev_i32_e32 v169, 31, v168
	v_lshl_add_u64 v[128:129], v[174:175], 2, s[8:9]
	v_lshl_add_u64 v[166:167], v[168:169], 2, s[12:13]
	global_load_dword v176, v[166:167], off
	global_load_dword v222, v[166:167], off offset:64
	global_load_dword v224, v[166:167], off offset:128
	global_load_dword v226, v[166:167], off offset:192
	global_load_dword v228, v[166:167], off offset:512
	global_load_dword v230, v[166:167], off offset:576
	global_load_dword v232, v[166:167], off offset:640
	global_load_dword v234, v[166:167], off offset:704
	global_load_dwordx4 v[140:143], v[128:129], off
	global_load_dwordx4 v[136:139], v[128:129], off offset:16
	global_load_dwordx4 v[132:135], v[128:129], off offset:512
	s_nop 0
	global_load_dwordx4 v[128:131], v[128:129], off offset:528
	s_ashr_i32 s6, s6, 6
	s_ashr_i32 s30, s7, 6
	s_ashr_i32 s7, s6, 31
	s_ashr_i32 s31, s30, 31
	s_lshl_b64 s[28:29], s[30:31], 13
	s_lshl_b64 s[34:35], s[6:7], 22
	s_add_u32 s28, s53, s28
	s_addc_u32 s29, s54, s29
	s_add_u32 s6, s28, s34
	v_lshlrev_b32_e32 v154, 7, v174
	s_addc_u32 s7, s29, s35
	s_or_b32 s30, s30, 2
	v_and_b32_e32 v154, 0x1c00, v154
	s_ashr_i32 s31, s30, 31
	v_lshl_add_u64 v[180:181], s[6:7], 0, v[154:155]
	s_lshl_b64 s[6:7], s[30:31], 13
	s_add_u32 s6, s53, s6
	s_addc_u32 s7, s54, s7
	s_add_u32 s30, s6, s34
	s_addc_u32 s31, s7, s35
	v_mov_b32_e32 v165, v155
	v_or_b32_e32 v174, 16, v168
	v_lshl_add_u64 v[184:185], s[30:31], 0, v[154:155]
	v_ashrrev_i32_e32 v175, 31, v174
	v_lshl_add_u64 v[182:183], v[180:181], 0, v[164:165]
	v_lshl_add_u64 v[186:187], v[184:185], 0, v[164:165]
	v_lshl_add_u64 v[178:179], v[174:175], 2, s[12:13]
	s_andn2_b64 vcc, exec, s[0:1]
	s_mov_b64 s[0:1], -1
	s_waitcnt vmcnt(0)
	v_pk_fma_f32 v[126:127], v[126:127], v[142:143], v[176:177] op_sel_hi:[1,1,0]
	v_pk_fma_f32 v[124:125], v[124:125], v[140:141], v[176:177] op_sel_hi:[1,1,0]
	v_pk_fma_f32 v[122:123], v[122:123], v[138:139], v[176:177] op_sel_hi:[1,1,0]
	v_pk_fma_f32 v[120:121], v[120:121], v[136:137], v[176:177] op_sel_hi:[1,1,0]
	v_pk_fma_f32 v[118:119], v[118:119], v[134:135], v[176:177] op_sel_hi:[1,1,0]
	v_pk_fma_f32 v[116:117], v[116:117], v[132:133], v[176:177] op_sel_hi:[1,1,0]
	v_pk_fma_f32 v[188:189], v[114:115], v[130:131], v[176:177] op_sel_hi:[1,1,0]
	v_pk_fma_f32 v[176:177], v[112:113], v[128:129], v[176:177] op_sel_hi:[1,1,0]
	v_cvt_pk_bf16_f32 v112, v124, v125
	v_cvt_pk_bf16_f32 v113, v126, v127
	v_cvt_pk_bf16_f32 v114, v120, v121
	v_cvt_pk_bf16_f32 v115, v122, v123
	global_store_dwordx4 v[182:183], v[112:115], off
	s_nop 1
	v_cvt_pk_bf16_f32 v112, v116, v117
	v_cvt_pk_bf16_f32 v113, v118, v119
	v_cvt_pk_bf16_f32 v114, v176, v177
	v_cvt_pk_bf16_f32 v115, v188, v189
	global_store_dwordx4 v[186:187], v[112:115], off
	s_nop 1
	v_or_b32_e32 v116, 32, v168
	v_lshlrev_b32_e32 v113, 4, v174
	v_mov_b32_e32 v115, v155
	v_and_b32_e32 v114, 0x1f0, v113
	v_ashrrev_i32_e32 v117, 31, v116
	v_lshl_add_u64 v[120:121], v[180:181], 0, v[114:115]
	v_lshl_add_u64 v[114:115], v[184:185], 0, v[114:115]
	v_lshl_add_u64 v[118:119], v[116:117], 2, s[12:13]
	v_pk_fma_f32 v[110:111], v[110:111], v[142:143], v[222:223] op_sel_hi:[1,1,0]
	v_pk_fma_f32 v[108:109], v[108:109], v[140:141], v[222:223] op_sel_hi:[1,1,0]
	v_pk_fma_f32 v[106:107], v[106:107], v[138:139], v[222:223] op_sel_hi:[1,1,0]
	v_pk_fma_f32 v[104:105], v[104:105], v[136:137], v[222:223] op_sel_hi:[1,1,0]
	v_pk_fma_f32 v[102:103], v[102:103], v[134:135], v[222:223] op_sel_hi:[1,1,0]
	v_pk_fma_f32 v[100:101], v[100:101], v[132:133], v[222:223] op_sel_hi:[1,1,0]
	v_pk_fma_f32 v[122:123], v[98:99], v[130:131], v[222:223] op_sel_hi:[1,1,0]
	v_pk_fma_f32 v[112:113], v[96:97], v[128:129], v[222:223] op_sel_hi:[1,1,0]
	v_cvt_pk_bf16_f32 v96, v108, v109
	v_cvt_pk_bf16_f32 v97, v110, v111
	v_cvt_pk_bf16_f32 v98, v104, v105
	v_cvt_pk_bf16_f32 v99, v106, v107
	global_store_dwordx4 v[120:121], v[96:99], off
	s_nop 1
	v_cvt_pk_bf16_f32 v96, v100, v101
	v_cvt_pk_bf16_f32 v97, v102, v103
	v_cvt_pk_bf16_f32 v98, v112, v113
	v_cvt_pk_bf16_f32 v99, v122, v123
	global_store_dwordx4 v[114:115], v[96:99], off
	s_nop 1
	v_or_b32_e32 v100, 48, v168
	v_lshlrev_b32_e32 v97, 4, v116
	v_mov_b32_e32 v99, v155
	v_and_b32_e32 v98, 0x2f0, v97
	v_ashrrev_i32_e32 v101, 31, v100
	v_lshl_add_u64 v[104:105], v[180:181], 0, v[98:99]
	v_lshl_add_u64 v[98:99], v[184:185], 0, v[98:99]
	v_lshl_add_u64 v[102:103], v[100:101], 2, s[12:13]
	v_pk_fma_f32 v[94:95], v[94:95], v[142:143], v[224:225] op_sel_hi:[1,1,0]
	v_pk_fma_f32 v[92:93], v[92:93], v[140:141], v[224:225] op_sel_hi:[1,1,0]
	v_pk_fma_f32 v[90:91], v[90:91], v[138:139], v[224:225] op_sel_hi:[1,1,0]
	v_pk_fma_f32 v[88:89], v[88:89], v[136:137], v[224:225] op_sel_hi:[1,1,0]
	v_pk_fma_f32 v[86:87], v[86:87], v[134:135], v[224:225] op_sel_hi:[1,1,0]
	v_pk_fma_f32 v[84:85], v[84:85], v[132:133], v[224:225] op_sel_hi:[1,1,0]
	v_pk_fma_f32 v[106:107], v[82:83], v[130:131], v[224:225] op_sel_hi:[1,1,0]
	v_pk_fma_f32 v[96:97], v[80:81], v[128:129], v[224:225] op_sel_hi:[1,1,0]
	v_cvt_pk_bf16_f32 v80, v92, v93
	v_cvt_pk_bf16_f32 v81, v94, v95
	v_cvt_pk_bf16_f32 v82, v88, v89
	v_cvt_pk_bf16_f32 v83, v90, v91
	global_store_dwordx4 v[104:105], v[80:83], off
	s_nop 1
	v_cvt_pk_bf16_f32 v80, v84, v85
	v_cvt_pk_bf16_f32 v81, v86, v87
	v_cvt_pk_bf16_f32 v82, v96, v97
	v_cvt_pk_bf16_f32 v83, v106, v107
	global_store_dwordx4 v[98:99], v[80:83], off
	s_nop 1
	s_nop 0
	v_lshlrev_b32_e32 v81, 4, v100
	v_mov_b32_e32 v83, v155
; __device__ __forceinline__ u32x4v pack8(const f32x4& a, const f32x4& b) { u32x4v w; w.x = cvt_pk_bf16(a[0], a[1]); w.y = cvt_pk_bf16(a[2], a[3]); w.z = cvt_pk_bf16(b[0], b[1]); w.w = cvt_pk_bf16(b[2], b[3]); return w; }
;     __device__ __forceinline__ void operator()(const f32x4 (&acc)[2][2][4][2], const Unit& u, int wr, int wc, int fr, int fq) const {
;     ...
;             for (int m = 0; m < 4; ++m) { const int r = row0 + ai * HALF + m * 16; const float rv = rvec[r]; bf16_t* rowp = O + (size_t)r * ldc + col0;
;                 const float rk = (MODE == 2) ? fabsf(rv) * kdec : 0.f;
; #pragma unroll
;                 for (int bj = 0; bj < 2; ++bj) { f32x4 v0 = acc[ai][bj][m][0], v1 = acc[ai][bj][m][1];
;                     if (MODE == 0) { v0 = v0 + rv; v1 = v1 + rv; }
;                     if (MODE == 1) { v0 = v0 * cs[bj][0] + rv; v1 = v1 * cs[bj][1] + rv; }
;                     if (MODE == 2) { const float cb = (float)(col0 + bj * HALF);
; #pragma unroll
;                         for (int e = 0; e < 4; ++e) { v0[e] *= __builtin_amdgcn_exp2f(-(cb + (float)e) * rk); v1[e] *= __builtin_amdgcn_exp2f(-(cb + (float)(4 + e)) * rk); } }
;                     if (MODE == 1) {
;                         const int mtok = col0 + bj * HALF; const size_t o = ((((size_t)(r >> 6) * 512 + (mtok >> 6)) * 8 + ((mtok & 63) >> 3)) * 64 + (r & 63)) * 8;
;                         *(u32x4v*)(O + o) = pack8(v0, v1);
	v_and_b32_e32 v82, 0x3f0, v81
	v_lshl_add_u64 v[84:85], v[180:181], 0, v[82:83]
	v_lshl_add_u64 v[82:83], v[184:185], 0, v[82:83]
	v_pk_fma_f32 v[78:79], v[78:79], v[142:143], v[226:227] op_sel_hi:[1,1,0]
	v_pk_fma_f32 v[76:77], v[76:77], v[140:141], v[226:227] op_sel_hi:[1,1,0]
	v_pk_fma_f32 v[74:75], v[74:75], v[138:139], v[226:227] op_sel_hi:[1,1,0]
	v_pk_fma_f32 v[72:73], v[72:73], v[136:137], v[226:227] op_sel_hi:[1,1,0]
	v_pk_fma_f32 v[70:71], v[70:71], v[134:135], v[226:227] op_sel_hi:[1,1,0]
	v_pk_fma_f32 v[68:69], v[68:69], v[132:133], v[226:227] op_sel_hi:[1,1,0]
	v_pk_fma_f32 v[86:87], v[66:67], v[130:131], v[226:227] op_sel_hi:[1,1,0]
	v_pk_fma_f32 v[80:81], v[64:65], v[128:129], v[226:227] op_sel_hi:[1,1,0]
	v_cvt_pk_bf16_f32 v64, v76, v77
	v_cvt_pk_bf16_f32 v65, v78, v79
	v_cvt_pk_bf16_f32 v66, v72, v73
	v_cvt_pk_bf16_f32 v67, v74, v75
	global_store_dwordx4 v[84:85], v[64:67], off
	s_nop 1
	v_cvt_pk_bf16_f32 v64, v68, v69
	v_cvt_pk_bf16_f32 v65, v70, v71
	v_cvt_pk_bf16_f32 v66, v80, v81
	v_cvt_pk_bf16_f32 v67, v86, v87
	global_store_dwordx4 v[82:83], v[64:67], off
	s_nop 1
	v_pk_fma_f32 v[62:63], v[62:63], v[142:143], v[228:229] op_sel_hi:[1,1,0]
	v_add_u32_e32 v64, 0x80, v168
	v_ashrrev_i32_e32 v64, 6, v64
	v_ashrrev_i32_e32 v65, 31, v64
	v_lshlrev_b64 v[68:69], 22, v[64:65]
	v_lshl_add_u64 v[64:65], s[28:29], 0, v[68:69]
	v_lshl_add_u64 v[68:69], s[6:7], 0, v[68:69]
	v_lshl_add_u64 v[64:65], v[64:65], 0, v[154:155]
	v_lshl_add_u64 v[68:69], v[68:69], 0, v[154:155]
	v_lshl_add_u64 v[70:71], v[64:65], 0, v[164:165]
	v_lshl_add_u64 v[72:73], v[68:69], 0, v[164:165]
	v_pk_fma_f32 v[60:61], v[60:61], v[140:141], v[228:229] op_sel_hi:[1,1,0]
	v_pk_fma_f32 v[58:59], v[58:59], v[138:139], v[228:229] op_sel_hi:[1,1,0]
	v_pk_fma_f32 v[56:57], v[56:57], v[136:137], v[228:229] op_sel_hi:[1,1,0]
	v_pk_fma_f32 v[54:55], v[54:55], v[134:135], v[228:229] op_sel_hi:[1,1,0]
	v_pk_fma_f32 v[52:53], v[52:53], v[132:133], v[228:229] op_sel_hi:[1,1,0]
	v_pk_fma_f32 v[74:75], v[50:51], v[130:131], v[228:229] op_sel_hi:[1,1,0]
	v_pk_fma_f32 v[66:67], v[48:49], v[128:129], v[228:229] op_sel_hi:[1,1,0]
	v_cvt_pk_bf16_f32 v48, v60, v61
	v_cvt_pk_bf16_f32 v49, v62, v63
	v_cvt_pk_bf16_f32 v50, v56, v57
	v_cvt_pk_bf16_f32 v51, v58, v59
	global_store_dwordx4 v[70:71], v[48:51], off
	v_lshlrev_b32_e32 v56, 4, v168
	s_nop 0
	v_cvt_pk_bf16_f32 v48, v52, v53
	v_cvt_pk_bf16_f32 v49, v54, v55
	v_cvt_pk_bf16_f32 v50, v66, v67
	v_cvt_pk_bf16_f32 v51, v74, v75
	global_store_dwordx4 v[72:73], v[48:51], off
	s_nop 1
	s_nop 0
	v_add_u32_e32 v49, 0x900, v56
	v_and_b32_e32 v154, 0x1f0, v49
	v_lshl_add_u64 v[50:51], v[64:65], 0, v[154:155]
	v_lshl_add_u64 v[52:53], v[68:69], 0, v[154:155]
	v_pk_fma_f32 v[46:47], v[46:47], v[142:143], v[230:231] op_sel_hi:[1,1,0]
	v_pk_fma_f32 v[44:45], v[44:45], v[140:141], v[230:231] op_sel_hi:[1,1,0]
	v_pk_fma_f32 v[42:43], v[42:43], v[138:139], v[230:231] op_sel_hi:[1,1,0]
	v_pk_fma_f32 v[40:41], v[40:41], v[136:137], v[230:231] op_sel_hi:[1,1,0]
	v_pk_fma_f32 v[38:39], v[38:39], v[134:135], v[230:231] op_sel_hi:[1,1,0]
	v_pk_fma_f32 v[36:37], v[36:37], v[132:133], v[230:231] op_sel_hi:[1,1,0]
	v_pk_fma_f32 v[54:55], v[34:35], v[130:131], v[230:231] op_sel_hi:[1,1,0]
	v_pk_fma_f32 v[48:49], v[32:33], v[128:129], v[230:231] op_sel_hi:[1,1,0]
	v_cvt_pk_bf16_f32 v32, v44, v45
	v_cvt_pk_bf16_f32 v33, v46, v47
	v_cvt_pk_bf16_f32 v34, v40, v41
	v_cvt_pk_bf16_f32 v35, v42, v43
	global_store_dwordx4 v[50:51], v[32:35], off
	s_nop 1
	v_cvt_pk_bf16_f32 v32, v36, v37
	v_cvt_pk_bf16_f32 v33, v38, v39
	v_cvt_pk_bf16_f32 v34, v48, v49
	v_cvt_pk_bf16_f32 v35, v54, v55
	global_store_dwordx4 v[52:53], v[32:35], off
	s_nop 1
	s_nop 0
	v_add_u32_e32 v33, 0xa00, v56
	v_and_b32_e32 v154, 0x2f0, v33
	v_lshl_add_u64 v[34:35], v[64:65], 0, v[154:155]
	v_lshl_add_u64 v[36:37], v[68:69], 0, v[154:155]
	v_pk_fma_f32 v[30:31], v[30:31], v[142:143], v[232:233] op_sel_hi:[1,1,0]
	v_pk_fma_f32 v[28:29], v[28:29], v[140:141], v[232:233] op_sel_hi:[1,1,0]
	v_pk_fma_f32 v[26:27], v[26:27], v[138:139], v[232:233] op_sel_hi:[1,1,0]
	v_pk_fma_f32 v[24:25], v[24:25], v[136:137], v[232:233] op_sel_hi:[1,1,0]
	v_pk_fma_f32 v[22:23], v[22:23], v[134:135], v[232:233] op_sel_hi:[1,1,0]
	v_pk_fma_f32 v[20:21], v[20:21], v[132:133], v[232:233] op_sel_hi:[1,1,0]
	v_pk_fma_f32 v[38:39], v[18:19], v[130:131], v[232:233] op_sel_hi:[1,1,0]
	v_pk_fma_f32 v[32:33], v[16:17], v[128:129], v[232:233] op_sel_hi:[1,1,0]
	v_cvt_pk_bf16_f32 v16, v28, v29
	v_cvt_pk_bf16_f32 v17, v30, v31
	v_cvt_pk_bf16_f32 v18, v24, v25
	v_cvt_pk_bf16_f32 v19, v26, v27
	global_store_dwordx4 v[34:35], v[16:19], off
	s_nop 1
	v_cvt_pk_bf16_f32 v16, v20, v21
	v_cvt_pk_bf16_f32 v17, v22, v23
	v_cvt_pk_bf16_f32 v18, v32, v33
	v_cvt_pk_bf16_f32 v19, v38, v39
	global_store_dwordx4 v[36:37], v[16:19], off
	s_nop 1
	s_nop 0
	v_add_u32_e32 v17, 0xb00, v56
	v_and_b32_e32 v154, 0x3f0, v17
	v_lshl_add_u64 v[18:19], v[64:65], 0, v[154:155]
	v_lshl_add_u64 v[20:21], v[68:69], 0, v[154:155]
	v_pk_fma_f32 v[14:15], v[14:15], v[142:143], v[234:235] op_sel_hi:[1,1,0]
	v_pk_fma_f32 v[12:13], v[12:13], v[140:141], v[234:235] op_sel_hi:[1,1,0]
	v_pk_fma_f32 v[10:11], v[10:11], v[138:139], v[234:235] op_sel_hi:[1,1,0]
	v_pk_fma_f32 v[8:9], v[8:9], v[136:137], v[234:235] op_sel_hi:[1,1,0]
	v_pk_fma_f32 v[6:7], v[6:7], v[134:135], v[234:235] op_sel_hi:[1,1,0]
	v_pk_fma_f32 v[4:5], v[4:5], v[132:133], v[234:235] op_sel_hi:[1,1,0]
	v_pk_fma_f32 v[22:23], v[2:3], v[130:131], v[234:235] op_sel_hi:[1,1,0]
	v_pk_fma_f32 v[16:17], v[0:1], v[128:129], v[234:235] op_sel_hi:[1,1,0]
	v_cvt_pk_bf16_f32 v0, v12, v13
	v_cvt_pk_bf16_f32 v1, v14, v15
	v_cvt_pk_bf16_f32 v2, v8, v9
	v_cvt_pk_bf16_f32 v3, v10, v11
	global_store_dwordx4 v[18:19], v[0:3], off
	s_nop 1
	v_cvt_pk_bf16_f32 v0, v4, v5
	v_cvt_pk_bf16_f32 v1, v6, v7
	v_cvt_pk_bf16_f32 v2, v16, v17
	v_cvt_pk_bf16_f32 v3, v22, v23
	global_store_dwordx4 v[20:21], v[0:3], off
	s_cbranch_vccnz .LBB0_830
	s_andn2_b64 vcc, exec, s[10:11]
	s_cbranch_vccnz .LBB0_829
	s_barrier
	s_branch .LBB0_829
